# v62 + in-projection K-tile epilogue: kmax shuffles via permlane swaps / DPP moves instead of 40 ds_bpermute round trips
# speedup vs baseline: 1.0048x; 1.0048x over previous
; __device__ __forceinline__ unsigned pk_bf16(float lo, float hi) { f32x2 v = {lo, hi}; bf16x2_t b = __builtin_convertvector(v, bf16x2_t); return __builtin_bit_cast(unsigned, b); }
;     __device__ __forceinline__ void operator()(const f32x4 (&acc)[2][2][4][2], const Unit& u, int wr, int wc, int fr, int fq) const {
;     ...
;                     for (int m = 0; m < 4; ++m) {
;                         const int row = row0 + ai * HALF + m * 16;
;                         const float rv = rsqrtf(rowss[row] * (1.0f / 1024.0f) + 1e-6f);
;                         const f32x4 v0 = (acc[ai][bj][m][0] * rv + bz0) * qsc, v1 = (acc[ai][bj][m][1] * rv + bz1) * qsc;
;                         if (isk) { float s2 = (v0[0] * v0[0] + v0[1] * v0[1]) + (v0[2] * v0[2] + v0[3] * v0[3]) + (v1[0] * v1[0] + v1[1] * v1[1]) + (v1[2] * v1[2] + v1[3] * v1[3]);
;                             s2 += __shfl_xor(s2, 16); s2 += __shfl_xor(s2, 32); kmx = fmaxf(kmx, s2); }
;                         u32x4 w; w.x = pk_bf16(v0[0], v0[1]); w.y = pk_bf16(v0[2], v0[3]); w.z = pk_bf16(v1[0], v1[1]); w.w = pk_bf16(v1[2], v1[3]);
;                         *(u32x4*)(base + (size_t)row * pitch) = w;
.LBB0_277:
	v_lshl_add_u64 v[138:139], v[162:163], 2, s[12:13]
	global_load_dword v141, v[138:139], off
	global_load_dword v188, v[138:139], off offset:64
	global_load_dword v189, v[138:139], off offset:128
	global_load_dword v190, v[138:139], off offset:192
	global_load_dword v191, v[138:139], off offset:512
	global_load_dword v192, v[138:139], off offset:576
	global_load_dword v193, v[138:139], off offset:640
	global_load_dword v194, v[138:139], off offset:704
	global_load_dword v195, v[138:139], off offset:128
	global_load_dword v196, v[138:139], off offset:192
	global_load_dword v197, v[138:139], off offset:512
	global_load_dword v198, v[138:139], off offset:576
	global_load_dword v199, v[138:139], off offset:640
	global_load_dword v200, v[138:139], off offset:704
	s_cmp_eq_u32 s66, 1
	s_cselect_b64 s[68:69], -1, 0
	s_cmp_lg_u32 s66, 1
	s_waitcnt vmcnt(0)
	v_fmamk_f32 v141, v141, 0x3a800000, v227
	s_nop 1
	v_rsq_f32_e32 v141, v141
	s_nop 0
	v_mov_b32_e32 v168, v141
	v_pk_fma_f32 v[170:171], v[124:125], v[168:169], v[134:135] op_sel_hi:[1,0,1]
	v_pk_fma_f32 v[124:125], v[126:127], v[168:169], v[136:137] op_sel_hi:[1,0,1]
	v_pk_fma_f32 v[120:121], v[120:121], v[168:169], v[130:131] op_sel_hi:[1,0,1]
	v_pk_fma_f32 v[122:123], v[122:123], v[168:169], v[132:133] op_sel_hi:[1,0,1]
	v_pk_mul_f32 v[124:125], v[140:141], v[124:125] op_sel_hi:[0,1]
	v_pk_mul_f32 v[168:169], v[140:141], v[170:171] op_sel_hi:[0,1]
	v_pk_mul_f32 v[122:123], v[140:141], v[122:123] op_sel_hi:[0,1]
	v_pk_mul_f32 v[126:127], v[140:141], v[120:121] op_sel_hi:[0,1]
	v_mov_b32_e32 v159, 0
	s_cbranch_scc1 .LBB0_279
	v_pk_mul_f32 v[120:121], v[124:125], v[124:125]
	v_pk_mul_f32 v[170:171], v[168:169], v[168:169]
	v_and_b32_e32 v141, 64, v230
	v_pk_mov_b32 v[172:173], v[170:171], v[120:121] op_sel:[1,0]
	v_mov_b32_e32 v171, v121
	v_pk_add_f32 v[120:121], v[172:173], v[170:171]
	v_pk_mul_f32 v[170:171], v[122:123], v[122:123]
	v_pk_mul_f32 v[172:173], v[126:127], v[126:127]
	v_mov_b32_e32 v186, v170
	v_mov_b32_e32 v187, v172
	v_mov_b32_e32 v172, v171
	v_add_f32_e32 v120, v120, v121
	v_xor_b32_e32 v121, 16, v230
	v_add_u32_e32 v141, 64, v141
	v_pk_add_f32 v[170:171], v[186:187], v[172:173]
	v_cmp_lt_i32_e32 vcc, v121, v141
	v_add_f32_e32 v120, v171, v120
	v_add_f32_e32 v120, v170, v120
	v_cndmask_b32_e32 v121, v230, v121, vcc
	v_lshlrev_b32_e32 v121, 2, v121
	v_mov_b32_e32 v121, v120
	s_nop 1
	v_permlane16_swap_b32_e32 v121, v120
	s_waitcnt lgkmcnt(0)
	v_add_f32_e32 v120, v120, v121
	v_xor_b32_e32 v121, 32, v230
	v_cmp_lt_i32_e32 vcc, v121, v141
	s_nop 1
	v_cndmask_b32_e32 v121, v230, v121, vcc
	v_lshlrev_b32_e32 v121, 2, v121
	v_mov_b32_e32 v121, v120
	s_nop 1
	v_permlane32_swap_b32_e32 v121, v120
	s_waitcnt lgkmcnt(0)
	v_add_f32_e32 v120, v120, v121
	v_max_f32_e32 v159, 0, v120
.LBB0_279:
	s_lshl_b64 s[4:5], s[42:43], 1
	s_add_u32 s1, s2, s4
	s_addc_u32 s4, s3, s5
	s_lshl_b32 s0, s0, 1
	s_add_u32 s0, s1, s0
	s_addc_u32 s1, s4, 0
	s_lshl_b32 s59, s91, 1
	s_add_u32 s0, s0, s59
	s_addc_u32 s1, s1, 0
	v_lshl_add_u64 v[120:121], v[164:165], 1, s[0:1]
	v_cvt_pk_bf16_f32 v171, v122, v123
	v_mad_i64_i32 v[122:123], s[0:1], s74, v162, 0
	v_cvt_pk_bf16_f32 v168, v168, v169
	v_cvt_pk_bf16_f32 v169, v124, v125
	v_cvt_pk_bf16_f32 v170, v126, v127
	v_lshl_add_u64 v[122:123], v[122:123], 1, v[120:121]
	global_store_dwordx4 v[122:123], v[168:171], off
	s_nop 0
	v_mov_b32_e32 v141, v140
	v_mov_b32_e32 v122, v140
	v_mov_b32_e32 v123, v140
	s_andn2_b64 vcc, exec, s[68:69]
	v_fmamk_f32 v124, v188, 0x3a800000, v227
	s_nop 1
	v_rsq_f32_e32 v124, v124
	v_cndmask_b32_e64 v125, 0, 1, s[68:69]
	v_cmp_ne_u32_e64 s[42:43], 1, v125
	v_pk_fma_f32 v[116:117], v[116:117], v[124:125], v[134:135] op_sel_hi:[1,0,1]
	v_pk_fma_f32 v[118:119], v[118:119], v[124:125], v[136:137] op_sel_hi:[1,0,1]
	v_pk_fma_f32 v[126:127], v[112:113], v[124:125], v[130:131] op_sel_hi:[1,0,1]
	v_pk_fma_f32 v[112:113], v[114:115], v[124:125], v[132:133] op_sel_hi:[1,0,1]
	v_pk_mul_f32 v[114:115], v[122:123], v[118:119]
	v_pk_mul_f32 v[118:119], v[140:141], v[116:117]
	v_pk_mul_f32 v[112:113], v[122:123], v[112:113]
	v_pk_mul_f32 v[116:117], v[140:141], v[126:127]
	s_cbranch_vccnz .LBB0_281
	v_pk_mul_f32 v[124:125], v[114:115], v[114:115]
	v_pk_mul_f32 v[126:127], v[118:119], v[118:119]
	s_nop 0
	v_pk_mov_b32 v[168:169], v[126:127], v[124:125] op_sel:[1,0]
	v_mov_b32_e32 v127, v125
	v_pk_add_f32 v[124:125], v[168:169], v[126:127]
	v_pk_mul_f32 v[126:127], v[112:113], v[112:113]
	v_pk_mul_f32 v[168:169], v[116:117], v[116:117]
	v_mov_b32_e32 v170, v126
	v_mov_b32_e32 v171, v168
	v_mov_b32_e32 v168, v127
	v_pk_add_f32 v[126:127], v[170:171], v[168:169]
	v_add_f32_e32 v124, v124, v125
	v_add_f32_e32 v124, v127, v124
	v_add_f32_e32 v124, v126, v124
	v_and_b32_e32 v126, 64, v230
	v_xor_b32_e32 v125, 16, v230
	v_add_u32_e32 v126, 64, v126
	v_cmp_lt_i32_e32 vcc, v125, v126
	s_nop 1
	v_cndmask_b32_e32 v125, v230, v125, vcc
	v_lshlrev_b32_e32 v125, 2, v125
	v_mov_b32_e32 v125, v124
	s_nop 1
	v_permlane16_swap_b32_e32 v125, v124
	s_waitcnt lgkmcnt(0)
	v_add_f32_e32 v124, v124, v125
	v_xor_b32_e32 v125, 32, v230
	v_cmp_lt_i32_e32 vcc, v125, v126
	s_nop 1
	v_cndmask_b32_e32 v125, v230, v125, vcc
	v_lshlrev_b32_e32 v125, 2, v125
	v_mov_b32_e32 v125, v124
	s_nop 1
	v_permlane32_swap_b32_e32 v125, v124
	s_waitcnt lgkmcnt(0)
	v_add_f32_e32 v124, v124, v125
	v_max_f32_e32 v125, v159, v159
	v_max_f32_e32 v159, v125, v124
; __device__ __forceinline__ unsigned pk_bf16(float lo, float hi) { f32x2 v = {lo, hi}; bf16x2_t b = __builtin_convertvector(v, bf16x2_t); return __builtin_bit_cast(unsigned, b); }
;     __device__ __forceinline__ void operator()(const f32x4 (&acc)[2][2][4][2], const Unit& u, int wr, int wc, int fr, int fq) const {
;     ...
;                     for (int m = 0; m < 4; ++m) {
;                         const int row = row0 + ai * HALF + m * 16;
;                         const float rv = rsqrtf(rowss[row] * (1.0f / 1024.0f) + 1e-6f);
;                         const f32x4 v0 = (acc[ai][bj][m][0] * rv + bz0) * qsc, v1 = (acc[ai][bj][m][1] * rv + bz1) * qsc;
;                         if (isk) { float s2 = (v0[0] * v0[0] + v0[1] * v0[1]) + (v0[2] * v0[2] + v0[3] * v0[3]) + (v1[0] * v1[0] + v1[1] * v1[1]) + (v1[2] * v1[2] + v1[3] * v1[3]);
;                             s2 += __shfl_xor(s2, 16); s2 += __shfl_xor(s2, 32); kmx = fmaxf(kmx, s2); }
;                         u32x4 w; w.x = pk_bf16(v0[0], v0[1]); w.y = pk_bf16(v0[2], v0[3]); w.z = pk_bf16(v1[0], v1[1]); w.w = pk_bf16(v1[2], v1[3]);
;                         *(u32x4*)(base + (size_t)row * pitch) = w;
.LBB0_281:
	v_cvt_pk_bf16_f32 v127, v112, v113
	v_mad_i64_i32 v[112:113], s[0:1], s74, v243, 0
	v_cvt_pk_bf16_f32 v124, v118, v119
	v_cvt_pk_bf16_f32 v125, v114, v115
	v_cvt_pk_bf16_f32 v126, v116, v117
	v_lshl_add_u64 v[112:113], v[112:113], 1, v[120:121]
	global_store_dwordx4 v[112:113], v[124:127], off
	s_nop 0
	s_and_b64 vcc, exec, s[42:43]
	v_fmamk_f32 v112, v189, 0x3a800000, v227
	s_nop 1
	v_rsq_f32_e32 v112, v112
	s_nop 0
	v_pk_fma_f32 v[108:109], v[108:109], v[112:113], v[134:135] op_sel_hi:[1,0,1]
	v_pk_fma_f32 v[110:111], v[110:111], v[112:113], v[136:137] op_sel_hi:[1,0,1]
	v_pk_fma_f32 v[114:115], v[104:105], v[112:113], v[130:131] op_sel_hi:[1,0,1]
	v_pk_fma_f32 v[104:105], v[106:107], v[112:113], v[132:133] op_sel_hi:[1,0,1]
	v_pk_mul_f32 v[106:107], v[122:123], v[110:111]
	v_pk_mul_f32 v[110:111], v[140:141], v[108:109]
	v_pk_mul_f32 v[104:105], v[122:123], v[104:105]
	v_pk_mul_f32 v[108:109], v[140:141], v[114:115]
	s_cbranch_vccnz .LBB0_283
	v_pk_mul_f32 v[112:113], v[106:107], v[106:107]
	v_pk_mul_f32 v[114:115], v[110:111], v[110:111]
	s_nop 0
	v_pk_mov_b32 v[116:117], v[114:115], v[112:113] op_sel:[1,0]
	v_mov_b32_e32 v115, v113
	v_pk_add_f32 v[112:113], v[116:117], v[114:115]
	v_pk_mul_f32 v[114:115], v[104:105], v[104:105]
	v_pk_mul_f32 v[116:117], v[108:109], v[108:109]
	v_mov_b32_e32 v118, v114
	v_mov_b32_e32 v119, v116
	v_mov_b32_e32 v116, v115
	v_pk_add_f32 v[114:115], v[118:119], v[116:117]
	v_add_f32_e32 v112, v112, v113
	v_add_f32_e32 v112, v115, v112
	v_add_f32_e32 v112, v114, v112
	v_and_b32_e32 v114, 64, v230
	v_xor_b32_e32 v113, 16, v230
	v_add_u32_e32 v114, 64, v114
	v_cmp_lt_i32_e32 vcc, v113, v114
	s_nop 1
	v_cndmask_b32_e32 v113, v230, v113, vcc
	v_lshlrev_b32_e32 v113, 2, v113
	v_mov_b32_e32 v113, v112
	s_nop 1
	v_permlane16_swap_b32_e32 v113, v112
	s_waitcnt lgkmcnt(0)
	v_add_f32_e32 v112, v112, v113
	v_xor_b32_e32 v113, 32, v230
	v_cmp_lt_i32_e32 vcc, v113, v114
	s_nop 1
	v_cndmask_b32_e32 v113, v230, v113, vcc
	v_lshlrev_b32_e32 v113, 2, v113
	v_mov_b32_e32 v113, v112
	s_nop 1
	v_permlane32_swap_b32_e32 v113, v112
	s_waitcnt lgkmcnt(0)
	v_add_f32_e32 v112, v112, v113
	v_max_f32_e32 v113, v159, v159
	v_max_f32_e32 v159, v113, v112
.LBB0_283:
	v_cvt_pk_bf16_f32 v113, v104, v105
	v_mad_i64_i32 v[104:105], s[0:1], s74, v242, 0
	v_cvt_pk_bf16_f32 v110, v110, v111
	v_cvt_pk_bf16_f32 v111, v106, v107
	v_cvt_pk_bf16_f32 v112, v108, v109
	v_lshl_add_u64 v[104:105], v[104:105], 1, v[120:121]
	global_store_dwordx4 v[104:105], v[110:113], off
	s_nop 0
	s_and_b64 vcc, exec, s[42:43]
	v_fmamk_f32 v104, v190, 0x3a800000, v227
	s_nop 1
	v_rsq_f32_e32 v106, v104
	v_mov_b32_e32 v104, v140
	v_mov_b32_e32 v105, v140
	v_pk_fma_f32 v[100:101], v[100:101], v[106:107], v[134:135] op_sel_hi:[1,0,1]
	v_pk_fma_f32 v[102:103], v[102:103], v[106:107], v[136:137] op_sel_hi:[1,0,1]
	v_pk_fma_f32 v[108:109], v[96:97], v[106:107], v[130:131] op_sel_hi:[1,0,1]
	v_pk_fma_f32 v[96:97], v[98:99], v[106:107], v[132:133] op_sel_hi:[1,0,1]
	v_pk_mul_f32 v[98:99], v[104:105], v[102:103]
	v_pk_mul_f32 v[102:103], v[140:141], v[100:101]
	v_pk_mul_f32 v[96:97], v[104:105], v[96:97]
	v_pk_mul_f32 v[100:101], v[140:141], v[108:109]
	s_cbranch_vccnz .LBB0_285
	v_pk_mul_f32 v[106:107], v[98:99], v[98:99]
	v_pk_mul_f32 v[108:109], v[102:103], v[102:103]
	s_nop 0
	v_pk_mov_b32 v[110:111], v[108:109], v[106:107] op_sel:[1,0]
	v_mov_b32_e32 v109, v107
	v_pk_add_f32 v[106:107], v[110:111], v[108:109]
	v_pk_mul_f32 v[108:109], v[96:97], v[96:97]
	v_pk_mul_f32 v[110:111], v[100:101], v[100:101]
	v_mov_b32_e32 v112, v108
	v_mov_b32_e32 v113, v110
	v_mov_b32_e32 v110, v109
	v_pk_add_f32 v[108:109], v[112:113], v[110:111]
	v_add_f32_e32 v106, v106, v107
	v_add_f32_e32 v106, v109, v106
	v_add_f32_e32 v106, v108, v106
	v_and_b32_e32 v108, 64, v230
	v_xor_b32_e32 v107, 16, v230
	v_add_u32_e32 v108, 64, v108
	v_cmp_lt_i32_e32 vcc, v107, v108
	s_nop 1
	v_cndmask_b32_e32 v107, v230, v107, vcc
	v_lshlrev_b32_e32 v107, 2, v107
	v_mov_b32_e32 v107, v106
	s_nop 1
	v_permlane16_swap_b32_e32 v107, v106
	s_waitcnt lgkmcnt(0)
	v_add_f32_e32 v106, v106, v107
	v_xor_b32_e32 v107, 32, v230
	v_cmp_lt_i32_e32 vcc, v107, v108
	s_nop 1
	v_cndmask_b32_e32 v107, v230, v107, vcc
	v_lshlrev_b32_e32 v107, 2, v107
	v_mov_b32_e32 v107, v106
	s_nop 1
	v_permlane32_swap_b32_e32 v107, v106
	s_waitcnt lgkmcnt(0)
	v_add_f32_e32 v106, v106, v107
	v_max_f32_e32 v107, v159, v159
	v_max_f32_e32 v159, v107, v106
.LBB0_285:
	v_cvt_pk_bf16_f32 v109, v96, v97
	v_mad_i64_i32 v[96:97], s[0:1], s74, v241, 0
	v_cvt_pk_bf16_f32 v106, v102, v103
	v_cvt_pk_bf16_f32 v107, v98, v99
	v_cvt_pk_bf16_f32 v108, v100, v101
	v_lshl_add_u64 v[96:97], v[96:97], 1, v[120:121]
	global_store_dwordx4 v[96:97], v[106:109], off
	s_nop 0
	s_and_b64 vcc, exec, s[42:43]
	v_fmamk_f32 v96, v191, 0x3a800000, v227
	s_nop 1
	v_rsq_f32_e32 v96, v96
	s_nop 0
	v_pk_fma_f32 v[92:93], v[92:93], v[96:97], v[134:135] op_sel_hi:[1,0,1]
	v_pk_fma_f32 v[94:95], v[94:95], v[96:97], v[136:137] op_sel_hi:[1,0,1]
	v_pk_fma_f32 v[98:99], v[88:89], v[96:97], v[130:131] op_sel_hi:[1,0,1]
	v_pk_fma_f32 v[88:89], v[90:91], v[96:97], v[132:133] op_sel_hi:[1,0,1]
	v_pk_mul_f32 v[90:91], v[104:105], v[94:95]
	v_pk_mul_f32 v[94:95], v[140:141], v[92:93]
	v_pk_mul_f32 v[88:89], v[104:105], v[88:89]
	v_pk_mul_f32 v[92:93], v[140:141], v[98:99]
	s_cbranch_vccnz .LBB0_287
	v_pk_mul_f32 v[96:97], v[90:91], v[90:91]
	v_pk_mul_f32 v[98:99], v[94:95], v[94:95]
	s_nop 0
	v_pk_mov_b32 v[100:101], v[98:99], v[96:97] op_sel:[1,0]
	v_mov_b32_e32 v99, v97
	v_pk_add_f32 v[96:97], v[100:101], v[98:99]
	v_pk_mul_f32 v[98:99], v[88:89], v[88:89]
	v_pk_mul_f32 v[100:101], v[92:93], v[92:93]
	v_mov_b32_e32 v102, v98
	v_mov_b32_e32 v103, v100
	v_mov_b32_e32 v100, v99
	v_pk_add_f32 v[98:99], v[102:103], v[100:101]
	v_add_f32_e32 v96, v96, v97
	v_add_f32_e32 v96, v99, v96
	v_add_f32_e32 v96, v98, v96
	v_and_b32_e32 v98, 64, v230
	v_xor_b32_e32 v97, 16, v230
	v_add_u32_e32 v98, 64, v98
	v_cmp_lt_i32_e32 vcc, v97, v98
	s_nop 1
	v_cndmask_b32_e32 v97, v230, v97, vcc
	v_lshlrev_b32_e32 v97, 2, v97
	v_mov_b32_e32 v97, v96
	s_nop 1
	v_permlane16_swap_b32_e32 v97, v96
	s_waitcnt lgkmcnt(0)
	v_add_f32_e32 v96, v96, v97
	v_xor_b32_e32 v97, 32, v230
	v_cmp_lt_i32_e32 vcc, v97, v98
	s_nop 1
	v_cndmask_b32_e32 v97, v230, v97, vcc
	v_lshlrev_b32_e32 v97, 2, v97
	v_mov_b32_e32 v97, v96
	s_nop 1
	v_permlane32_swap_b32_e32 v97, v96
	s_waitcnt lgkmcnt(0)
	v_add_f32_e32 v96, v96, v97
	v_max_f32_e32 v97, v159, v159
	v_max_f32_e32 v159, v97, v96
; __device__ __forceinline__ unsigned pk_bf16(float lo, float hi) { f32x2 v = {lo, hi}; bf16x2_t b = __builtin_convertvector(v, bf16x2_t); return __builtin_bit_cast(unsigned, b); }
;     __device__ __forceinline__ void operator()(const f32x4 (&acc)[2][2][4][2], const Unit& u, int wr, int wc, int fr, int fq) const {
;     ...
;                     for (int m = 0; m < 4; ++m) {
;                         const int row = row0 + ai * HALF + m * 16;
;                         const float rv = rsqrtf(rowss[row] * (1.0f / 1024.0f) + 1e-6f);
;                         const f32x4 v0 = (acc[ai][bj][m][0] * rv + bz0) * qsc, v1 = (acc[ai][bj][m][1] * rv + bz1) * qsc;
;                         if (isk) { float s2 = (v0[0] * v0[0] + v0[1] * v0[1]) + (v0[2] * v0[2] + v0[3] * v0[3]) + (v1[0] * v1[0] + v1[1] * v1[1]) + (v1[2] * v1[2] + v1[3] * v1[3]);
;                             s2 += __shfl_xor(s2, 16); s2 += __shfl_xor(s2, 32); kmx = fmaxf(kmx, s2); }
;                         u32x4 w; w.x = pk_bf16(v0[0], v0[1]); w.y = pk_bf16(v0[2], v0[3]); w.z = pk_bf16(v1[0], v1[1]); w.w = pk_bf16(v1[2], v1[3]);
;                         *(u32x4*)(base + (size_t)row * pitch) = w;
.LBB0_287:
	v_add_u32_e32 v96, 0x80, v162
	v_cvt_pk_bf16_f32 v101, v88, v89
	v_mad_i64_i32 v[88:89], s[0:1], s74, v96, 0
	v_cvt_pk_bf16_f32 v98, v94, v95
	v_cvt_pk_bf16_f32 v99, v90, v91
	v_cvt_pk_bf16_f32 v100, v92, v93
	v_lshl_add_u64 v[88:89], v[88:89], 1, v[120:121]
	global_store_dwordx4 v[88:89], v[98:101], off
	s_nop 0
	s_and_b64 vcc, exec, s[42:43]
	v_fmamk_f32 v88, v192, 0x3a800000, v227
	s_nop 1
	v_rsq_f32_e32 v90, v88
	v_mov_b32_e32 v88, v140
	v_mov_b32_e32 v89, v140
	v_pk_fma_f32 v[84:85], v[84:85], v[90:91], v[134:135] op_sel_hi:[1,0,1]
	v_pk_fma_f32 v[86:87], v[86:87], v[90:91], v[136:137] op_sel_hi:[1,0,1]
	v_pk_fma_f32 v[92:93], v[80:81], v[90:91], v[130:131] op_sel_hi:[1,0,1]
	v_pk_fma_f32 v[80:81], v[82:83], v[90:91], v[132:133] op_sel_hi:[1,0,1]
	v_pk_mul_f32 v[82:83], v[88:89], v[86:87]
	v_pk_mul_f32 v[86:87], v[140:141], v[84:85]
	v_pk_mul_f32 v[80:81], v[88:89], v[80:81]
	v_pk_mul_f32 v[84:85], v[140:141], v[92:93]
	s_cbranch_vccnz .LBB0_289
	v_pk_mul_f32 v[90:91], v[82:83], v[82:83]
	v_pk_mul_f32 v[92:93], v[86:87], v[86:87]
	s_nop 0
	v_pk_mov_b32 v[94:95], v[92:93], v[90:91] op_sel:[1,0]
	v_mov_b32_e32 v93, v91
	v_pk_add_f32 v[90:91], v[94:95], v[92:93]
	v_pk_mul_f32 v[92:93], v[80:81], v[80:81]
	v_pk_mul_f32 v[94:95], v[84:85], v[84:85]
	v_mov_b32_e32 v98, v92
	v_mov_b32_e32 v99, v94
	v_mov_b32_e32 v94, v93
	v_pk_add_f32 v[92:93], v[98:99], v[94:95]
	v_add_f32_e32 v90, v90, v91
	v_add_f32_e32 v90, v93, v90
	v_add_f32_e32 v90, v92, v90
	v_and_b32_e32 v92, 64, v230
	v_xor_b32_e32 v91, 16, v230
	v_add_u32_e32 v92, 64, v92
	v_cmp_lt_i32_e32 vcc, v91, v92
	s_nop 1
	v_cndmask_b32_e32 v91, v230, v91, vcc
	v_lshlrev_b32_e32 v91, 2, v91
	v_mov_b32_e32 v91, v90
	s_nop 1
	v_permlane16_swap_b32_e32 v91, v90
	s_waitcnt lgkmcnt(0)
	v_add_f32_e32 v90, v90, v91
	v_xor_b32_e32 v91, 32, v230
	v_cmp_lt_i32_e32 vcc, v91, v92
	s_nop 1
	v_cndmask_b32_e32 v91, v230, v91, vcc
	v_lshlrev_b32_e32 v91, 2, v91
	v_mov_b32_e32 v91, v90
	s_nop 1
	v_permlane32_swap_b32_e32 v91, v90
	s_waitcnt lgkmcnt(0)
	v_add_f32_e32 v90, v90, v91
	v_max_f32_e32 v91, v159, v159
	v_max_f32_e32 v159, v91, v90
.LBB0_289:
	v_add_u32_e32 v90, 0x90, v162
	v_cvt_pk_bf16_f32 v95, v80, v81
	v_mad_i64_i32 v[80:81], s[0:1], s74, v90, 0
	v_cvt_pk_bf16_f32 v92, v86, v87
	v_cvt_pk_bf16_f32 v93, v82, v83
	v_cvt_pk_bf16_f32 v94, v84, v85
	v_lshl_add_u64 v[80:81], v[80:81], 1, v[120:121]
	global_store_dwordx4 v[80:81], v[92:95], off
	s_nop 0
	s_and_b64 vcc, exec, s[42:43]
	v_fmamk_f32 v80, v193, 0x3a800000, v227
	s_nop 1
	v_rsq_f32_e32 v80, v80
	s_nop 0
	v_pk_fma_f32 v[76:77], v[76:77], v[80:81], v[134:135] op_sel_hi:[1,0,1]
	v_pk_fma_f32 v[78:79], v[78:79], v[80:81], v[136:137] op_sel_hi:[1,0,1]
	v_pk_fma_f32 v[82:83], v[72:73], v[80:81], v[130:131] op_sel_hi:[1,0,1]
	v_pk_fma_f32 v[72:73], v[74:75], v[80:81], v[132:133] op_sel_hi:[1,0,1]
	v_pk_mul_f32 v[74:75], v[88:89], v[78:79]
	v_pk_mul_f32 v[78:79], v[140:141], v[76:77]
	v_pk_mul_f32 v[72:73], v[88:89], v[72:73]
	v_pk_mul_f32 v[76:77], v[140:141], v[82:83]
	s_cbranch_vccnz .LBB0_291
	v_pk_mul_f32 v[80:81], v[74:75], v[74:75]
	v_pk_mul_f32 v[82:83], v[78:79], v[78:79]
	s_nop 0
	v_pk_mov_b32 v[84:85], v[82:83], v[80:81] op_sel:[1,0]
	v_mov_b32_e32 v83, v81
	v_pk_add_f32 v[80:81], v[84:85], v[82:83]
	v_pk_mul_f32 v[82:83], v[72:73], v[72:73]
	v_pk_mul_f32 v[84:85], v[76:77], v[76:77]
	v_mov_b32_e32 v86, v82
	v_mov_b32_e32 v87, v84
	v_mov_b32_e32 v84, v83
	v_pk_add_f32 v[82:83], v[86:87], v[84:85]
	v_add_f32_e32 v80, v80, v81
	v_add_f32_e32 v80, v83, v80
	v_add_f32_e32 v80, v82, v80
	v_and_b32_e32 v82, 64, v230
	v_xor_b32_e32 v81, 16, v230
	v_add_u32_e32 v82, 64, v82
	v_cmp_lt_i32_e32 vcc, v81, v82
	s_nop 1
	v_cndmask_b32_e32 v81, v230, v81, vcc
	v_lshlrev_b32_e32 v81, 2, v81
	v_mov_b32_e32 v81, v80
	s_nop 1
	v_permlane16_swap_b32_e32 v81, v80
	s_waitcnt lgkmcnt(0)
	v_add_f32_e32 v80, v80, v81
	v_xor_b32_e32 v81, 32, v230
	v_cmp_lt_i32_e32 vcc, v81, v82
	s_nop 1
	v_cndmask_b32_e32 v81, v230, v81, vcc
	v_lshlrev_b32_e32 v81, 2, v81
	v_mov_b32_e32 v81, v80
	s_nop 1
	v_permlane32_swap_b32_e32 v81, v80
	s_waitcnt lgkmcnt(0)
	v_add_f32_e32 v80, v80, v81
	v_max_f32_e32 v81, v159, v159
	v_max_f32_e32 v159, v81, v80
; __device__ __forceinline__ unsigned pk_bf16(float lo, float hi) { f32x2 v = {lo, hi}; bf16x2_t b = __builtin_convertvector(v, bf16x2_t); return __builtin_bit_cast(unsigned, b); }
;     __device__ __forceinline__ void operator()(const f32x4 (&acc)[2][2][4][2], const Unit& u, int wr, int wc, int fr, int fq) const {
;     ...
;                     for (int m = 0; m < 4; ++m) {
;                         const int row = row0 + ai * HALF + m * 16;
;                         const float rv = rsqrtf(rowss[row] * (1.0f / 1024.0f) + 1e-6f);
;                         const f32x4 v0 = (acc[ai][bj][m][0] * rv + bz0) * qsc, v1 = (acc[ai][bj][m][1] * rv + bz1) * qsc;
;                         if (isk) { float s2 = (v0[0] * v0[0] + v0[1] * v0[1]) + (v0[2] * v0[2] + v0[3] * v0[3]) + (v1[0] * v1[0] + v1[1] * v1[1]) + (v1[2] * v1[2] + v1[3] * v1[3]);
;                             s2 += __shfl_xor(s2, 16); s2 += __shfl_xor(s2, 32); kmx = fmaxf(kmx, s2); }
;                         u32x4 w; w.x = pk_bf16(v0[0], v0[1]); w.y = pk_bf16(v0[2], v0[3]); w.z = pk_bf16(v1[0], v1[1]); w.w = pk_bf16(v1[2], v1[3]);
;                         *(u32x4*)(base + (size_t)row * pitch) = w;
;                     }
;                 if (isk) { kmx = fmaxf(kmx, __shfl_xor(kmx, 1)); kmx = fmaxf(kmx, __shfl_xor(kmx, 2)); kmx = fmaxf(kmx, __shfl_xor(kmx, 4)); kmx = fmaxf(kmx, __shfl_xor(kmx, 8));
;                     if (fr == 0 && fqo == 0) { const int grp = pn == 1 ? 0 : 1; const int head = pn == 1 ? bj * 2 + (wc >> 1) : (wc >> 1);
;                         atomicMax(kmax + (grp * 4 + head) * 2 + (wc & 1), __float_as_uint(kmx * 1.02f)); } }
.LBB0_291:
	v_add_u32_e32 v80, 0xa0, v162
	v_cvt_pk_bf16_f32 v85, v72, v73
	v_mad_i64_i32 v[72:73], s[0:1], s74, v80, 0
	v_cvt_pk_bf16_f32 v82, v78, v79
	v_cvt_pk_bf16_f32 v83, v74, v75
	v_cvt_pk_bf16_f32 v84, v76, v77
	v_lshl_add_u64 v[72:73], v[72:73], 1, v[120:121]
	global_store_dwordx4 v[72:73], v[82:85], off
	s_nop 0
	s_and_b64 vcc, exec, s[42:43]
	v_fmamk_f32 v72, v194, 0x3a800000, v227
	s_nop 1
	v_rsq_f32_e32 v74, v72
	v_mov_b32_e32 v72, v140
	v_mov_b32_e32 v73, v140
	v_pk_fma_f32 v[68:69], v[68:69], v[74:75], v[134:135] op_sel_hi:[1,0,1]
	v_pk_fma_f32 v[70:71], v[70:71], v[74:75], v[136:137] op_sel_hi:[1,0,1]
	v_pk_fma_f32 v[76:77], v[64:65], v[74:75], v[130:131] op_sel_hi:[1,0,1]
	v_pk_fma_f32 v[64:65], v[66:67], v[74:75], v[132:133] op_sel_hi:[1,0,1]
	v_pk_mul_f32 v[66:67], v[72:73], v[70:71]
	v_pk_mul_f32 v[70:71], v[140:141], v[68:69]
	v_pk_mul_f32 v[64:65], v[72:73], v[64:65]
	v_pk_mul_f32 v[68:69], v[140:141], v[76:77]
	s_cbranch_vccnz .LBB0_293
	v_pk_mul_f32 v[72:73], v[66:67], v[66:67]
	v_pk_mul_f32 v[74:75], v[70:71], v[70:71]
	s_nop 0
	v_pk_mov_b32 v[76:77], v[74:75], v[72:73] op_sel:[1,0]
	v_mov_b32_e32 v75, v73
	v_pk_add_f32 v[72:73], v[76:77], v[74:75]
	v_pk_mul_f32 v[74:75], v[64:65], v[64:65]
	v_pk_mul_f32 v[76:77], v[68:69], v[68:69]
	v_mov_b32_e32 v78, v74
	v_mov_b32_e32 v79, v76
	v_mov_b32_e32 v76, v75
	v_pk_add_f32 v[74:75], v[78:79], v[76:77]
	v_add_f32_e32 v72, v72, v73
	v_add_f32_e32 v72, v75, v72
	v_add_f32_e32 v72, v74, v72
	v_and_b32_e32 v74, 64, v230
	v_xor_b32_e32 v73, 16, v230
	v_add_u32_e32 v74, 64, v74
	v_cmp_lt_i32_e32 vcc, v73, v74
	s_nop 1
	v_cndmask_b32_e32 v73, v230, v73, vcc
	v_lshlrev_b32_e32 v73, 2, v73
	v_mov_b32_e32 v73, v72
	s_nop 1
	v_permlane16_swap_b32_e32 v73, v72
	s_waitcnt lgkmcnt(0)
	v_add_f32_e32 v72, v72, v73
	v_xor_b32_e32 v73, 32, v230
	v_cmp_lt_i32_e32 vcc, v73, v74
	s_nop 1
	v_cndmask_b32_e32 v73, v230, v73, vcc
	v_lshlrev_b32_e32 v73, 2, v73
	v_mov_b32_e32 v73, v72
	s_nop 1
	v_permlane32_swap_b32_e32 v73, v72
	s_waitcnt lgkmcnt(0)
	v_add_f32_e32 v72, v72, v73
	v_max_f32_e32 v73, v159, v159
	v_max_f32_e32 v159, v73, v72
.LBB0_293:
	v_readlane_b32 s0, v255, 21
	v_cmp_eq_u32_e32 vcc, 0, v244
	v_readlane_b32 s1, v255, 22
	s_and_b64 s[70:71], s[0:1], vcc
	s_and_b64 s[0:1], s[68:69], exec
	v_add_u32_e32 v76, 0xb0, v162
	s_cselect_b32 s0, 0, 8
	v_readlane_b32 s1, v255, 20
	s_or_b32 s34, s0, s1
	v_cvt_pk_bf16_f32 v73, v64, v65
	v_mad_i64_i32 v[64:65], s[0:1], s74, v76, 0
	v_cvt_pk_bf16_f32 v70, v70, v71
	v_cvt_pk_bf16_f32 v71, v66, v67
	v_cvt_pk_bf16_f32 v72, v68, v69
	v_lshl_add_u64 v[64:65], v[64:65], 1, v[120:121]
	s_and_b64 vcc, exec, s[42:43]
	global_store_dwordx4 v[64:65], v[70:73], off
	s_cbranch_vccnz .LBB0_300
	v_and_b32_e32 v65, 64, v230
	v_xor_b32_e32 v64, 1, v230
	v_add_u32_e32 v65, 64, v65
	v_cmp_lt_i32_e32 vcc, v64, v65
	v_max_f32_e32 v66, v159, v159
	s_nop 0
	v_cndmask_b32_e32 v64, v230, v64, vcc
	v_lshlrev_b32_e32 v64, 2, v64
	s_nop 1
	v_mov_b32_dpp v64, v159 quad_perm:[1,0,3,2] row_mask:0xf bank_mask:0xf
	s_waitcnt lgkmcnt(0)
	v_max_f32_e32 v64, v64, v64
	v_max_f32_e32 v64, v66, v64
	v_xor_b32_e32 v66, 2, v230
	v_cmp_lt_i32_e32 vcc, v66, v65
	s_nop 1
	v_cndmask_b32_e32 v66, v230, v66, vcc
	v_lshlrev_b32_e32 v66, 2, v66
	s_nop 1
	v_mov_b32_dpp v66, v64 quad_perm:[2,3,0,1] row_mask:0xf bank_mask:0xf
	s_waitcnt lgkmcnt(0)
	v_max_f32_e32 v66, v66, v66
	v_max_f32_e32 v64, v64, v66
	v_xor_b32_e32 v66, 4, v230
	v_cmp_lt_i32_e32 vcc, v66, v65
	s_nop 1
	v_cndmask_b32_e32 v66, v230, v66, vcc
	v_lshlrev_b32_e32 v66, 2, v66
	s_nop 1
	v_mov_b32_dpp v66, v64 row_half_mirror row_mask:0xf bank_mask:0xf
	s_waitcnt lgkmcnt(0)
	v_max_f32_e32 v66, v66, v66
	v_max_f32_e32 v64, v64, v66
	v_xor_b32_e32 v66, 8, v230
	v_cmp_lt_i32_e32 vcc, v66, v65
	s_nop 1
	v_cndmask_b32_e32 v65, v230, v66, vcc
	v_lshlrev_b32_e32 v65, 2, v65
	s_nop 1
	v_mov_b32_dpp v65, v64 row_mirror row_mask:0xf bank_mask:0xf
	s_and_saveexec_b64 s[0:1], s[70:71]
	s_cbranch_execz .LBB0_299
	s_waitcnt lgkmcnt(0)
	v_max_f32_e32 v65, v65, v65
	v_max_f32_e32 v64, v64, v64
	v_max_f32_e32 v64, v64, v65
	s_mov_b64 s[4:5], exec
	v_mul_f32_e32 v64, 0x3f828f5c, v64
	s_mov_b32 s6, 0

; __device__ __forceinline__ unsigned pk_bf16(float lo, float hi) { f32x2 v = {lo, hi}; bf16x2_t b = __builtin_convertvector(v, bf16x2_t); return __builtin_bit_cast(unsigned, b); }
;     __device__ __forceinline__ void operator()(const f32x4 (&acc)[2][2][4][2], const Unit& u, int wr, int wc, int fr, int fq) const {
;     ...
;                     for (int m = 0; m < 4; ++m) {
;                         const int row = row0 + ai * HALF + m * 16;
;                         const float rv = rsqrtf(rowss[row] * (1.0f / 1024.0f) + 1e-6f);
;                         const f32x4 v0 = (acc[ai][bj][m][0] * rv + bz0) * qsc, v1 = (acc[ai][bj][m][1] * rv + bz1) * qsc;
;                         if (isk) { float s2 = (v0[0] * v0[0] + v0[1] * v0[1]) + (v0[2] * v0[2] + v0[3] * v0[3]) + (v1[0] * v1[0] + v1[1] * v1[1]) + (v1[2] * v1[2] + v1[3] * v1[3]);
;                             s2 += __shfl_xor(s2, 16); s2 += __shfl_xor(s2, 32); kmx = fmaxf(kmx, s2); }
;                         u32x4 w; w.x = pk_bf16(v0[0], v0[1]); w.y = pk_bf16(v0[2], v0[3]); w.z = pk_bf16(v1[0], v1[1]); w.w = pk_bf16(v1[2], v1[3]);
;                         *(u32x4*)(base + (size_t)row * pitch) = w;
.LBB0_313:
	v_rsq_f32_e32 v73, v72
	s_or_b64 vcc, s[74:75], s[4:5]
	v_cndmask_b32_e32 v72, 1.0, v231, vcc
	s_andn2_b64 vcc, exec, s[6:7]
	v_mov_b32_e32 v74, v73
	v_pk_fma_f32 v[78:79], v[60:61], v[74:75], v[68:69] op_sel_hi:[1,0,1]
	v_pk_fma_f32 v[60:61], v[62:63], v[74:75], v[70:71] op_sel_hi:[1,0,1]
	v_pk_fma_f32 v[56:57], v[56:57], v[74:75], v[64:65] op_sel_hi:[1,0,1]
	v_pk_fma_f32 v[58:59], v[58:59], v[74:75], v[66:67] op_sel_hi:[1,0,1]
	v_pk_mul_f32 v[60:61], v[72:73], v[60:61] op_sel_hi:[0,1]
	v_pk_mul_f32 v[62:63], v[72:73], v[78:79] op_sel_hi:[0,1]
	v_pk_mul_f32 v[58:59], v[72:73], v[58:59] op_sel_hi:[0,1]
	v_pk_mul_f32 v[74:75], v[72:73], v[56:57] op_sel_hi:[0,1]
	v_mov_b32_e32 v77, 0
	s_cbranch_vccnz .LBB0_315
	v_pk_mul_f32 v[56:57], v[60:61], v[60:61]
	v_pk_mul_f32 v[78:79], v[62:63], v[62:63]
	v_and_b32_e32 v73, 64, v230
	v_pk_mov_b32 v[82:83], v[78:79], v[56:57] op_sel:[1,0]
	v_mov_b32_e32 v79, v57
	v_pk_add_f32 v[56:57], v[82:83], v[78:79]
	v_pk_mul_f32 v[78:79], v[58:59], v[58:59]
	v_pk_mul_f32 v[82:83], v[74:75], v[74:75]
	v_mov_b32_e32 v84, v78
	v_mov_b32_e32 v85, v82
	v_mov_b32_e32 v82, v79
	v_add_f32_e32 v56, v56, v57
	v_xor_b32_e32 v57, 16, v230
	v_add_u32_e32 v73, 64, v73
	v_pk_add_f32 v[78:79], v[84:85], v[82:83]
	v_cmp_lt_i32_e32 vcc, v57, v73
	v_add_f32_e32 v56, v79, v56
	v_add_f32_e32 v56, v78, v56
	v_cndmask_b32_e32 v57, v230, v57, vcc
	v_lshlrev_b32_e32 v57, 2, v57
	v_mov_b32_e32 v57, v56
	s_nop 1
	v_permlane16_swap_b32_e32 v57, v56
	s_waitcnt lgkmcnt(0)
	v_add_f32_e32 v56, v56, v57
	v_xor_b32_e32 v57, 32, v230
	v_cmp_lt_i32_e32 vcc, v57, v73
	s_nop 1
	v_cndmask_b32_e32 v57, v230, v57, vcc
	v_lshlrev_b32_e32 v57, 2, v57
	v_mov_b32_e32 v57, v56
	s_nop 1
	v_permlane32_swap_b32_e32 v57, v56
	s_waitcnt lgkmcnt(0)
	v_add_f32_e32 v56, v56, v57
	v_max_f32_e32 v77, 0, v56

; __device__ __forceinline__ unsigned pk_bf16(float lo, float hi) { f32x2 v = {lo, hi}; bf16x2_t b = __builtin_convertvector(v, bf16x2_t); return __builtin_bit_cast(unsigned, b); }
;     __device__ __forceinline__ void operator()(const f32x4 (&acc)[2][2][4][2], const Unit& u, int wr, int wc, int fr, int fq) const {
;     ...
;                     for (int m = 0; m < 4; ++m) {
;                         const int row = row0 + ai * HALF + m * 16;
;                         const float rv = rsqrtf(rowss[row] * (1.0f / 1024.0f) + 1e-6f);
;                         const f32x4 v0 = (acc[ai][bj][m][0] * rv + bz0) * qsc, v1 = (acc[ai][bj][m][1] * rv + bz1) * qsc;
;                         if (isk) { float s2 = (v0[0] * v0[0] + v0[1] * v0[1]) + (v0[2] * v0[2] + v0[3] * v0[3]) + (v1[0] * v1[0] + v1[1] * v1[1]) + (v1[2] * v1[2] + v1[3] * v1[3]);
;                             s2 += __shfl_xor(s2, 16); s2 += __shfl_xor(s2, 32); kmx = fmaxf(kmx, s2); }
;                         u32x4 w; w.x = pk_bf16(v0[0], v0[1]); w.y = pk_bf16(v0[2], v0[3]); w.z = pk_bf16(v1[0], v1[1]); w.w = pk_bf16(v1[2], v1[3]);
;                         *(u32x4*)(base + (size_t)row * pitch) = w;
.LBB0_319:
	v_rsq_f32_e32 v60, v58
	v_mov_b32_e32 v58, v72
	v_mov_b32_e32 v59, v72
	s_andn2_b64 vcc, exec, s[4:5]
	v_pk_fma_f32 v[62:63], v[52:53], v[60:61], v[68:69] op_sel_hi:[1,0,1]
	v_pk_fma_f32 v[52:53], v[54:55], v[60:61], v[70:71] op_sel_hi:[1,0,1]
	v_pk_mul_f32 v[54:55], v[72:73], v[62:63]
	v_pk_fma_f32 v[62:63], v[48:49], v[60:61], v[64:65] op_sel_hi:[1,0,1]
	v_pk_fma_f32 v[48:49], v[50:51], v[60:61], v[66:67] op_sel_hi:[1,0,1]
	v_pk_mul_f32 v[52:53], v[58:59], v[52:53]
	v_pk_mul_f32 v[48:49], v[58:59], v[48:49]
	v_pk_mul_f32 v[50:51], v[72:73], v[62:63]
	s_cbranch_vccnz .LBB0_321
	v_pk_mul_f32 v[58:59], v[52:53], v[52:53]
	v_pk_mul_f32 v[60:61], v[54:55], v[54:55]
	s_nop 0
	v_pk_mov_b32 v[62:63], v[60:61], v[58:59] op_sel:[1,0]
	v_mov_b32_e32 v61, v59
	v_pk_add_f32 v[58:59], v[62:63], v[60:61]
	v_pk_mul_f32 v[60:61], v[48:49], v[48:49]
	v_pk_mul_f32 v[62:63], v[50:51], v[50:51]
	v_mov_b32_e32 v74, v60
	v_mov_b32_e32 v75, v62
	v_mov_b32_e32 v62, v61
	v_pk_add_f32 v[60:61], v[74:75], v[62:63]
	v_add_f32_e32 v58, v58, v59
	v_add_f32_e32 v58, v61, v58
	v_add_f32_e32 v58, v60, v58
	v_and_b32_e32 v60, 64, v230
	v_xor_b32_e32 v59, 16, v230
	v_add_u32_e32 v60, 64, v60
	v_cmp_lt_i32_e32 vcc, v59, v60
	s_nop 1
	v_cndmask_b32_e32 v59, v230, v59, vcc
	v_lshlrev_b32_e32 v59, 2, v59
	v_mov_b32_e32 v59, v58
	s_nop 1
	v_permlane16_swap_b32_e32 v59, v58
	s_waitcnt lgkmcnt(0)
	v_add_f32_e32 v58, v58, v59
	v_xor_b32_e32 v59, 32, v230
	v_cmp_lt_i32_e32 vcc, v59, v60
	s_nop 1
	v_cndmask_b32_e32 v59, v230, v59, vcc
	v_lshlrev_b32_e32 v59, 2, v59
	v_mov_b32_e32 v59, v58
	s_nop 1
	v_permlane32_swap_b32_e32 v59, v58
	s_waitcnt lgkmcnt(0)
	v_add_f32_e32 v58, v58, v59
	v_max_f32_e32 v59, v77, v77
	v_max_f32_e32 v77, v59, v58

; __device__ __forceinline__ unsigned pk_bf16(float lo, float hi) { f32x2 v = {lo, hi}; bf16x2_t b = __builtin_convertvector(v, bf16x2_t); return __builtin_bit_cast(unsigned, b); }
;     __device__ __forceinline__ void operator()(const f32x4 (&acc)[2][2][4][2], const Unit& u, int wr, int wc, int fr, int fq) const {
;     ...
;                     for (int m = 0; m < 4; ++m) {
;                         const int row = row0 + ai * HALF + m * 16;
;                         const float rv = rsqrtf(rowss[row] * (1.0f / 1024.0f) + 1e-6f);
;                         const f32x4 v0 = (acc[ai][bj][m][0] * rv + bz0) * qsc, v1 = (acc[ai][bj][m][1] * rv + bz1) * qsc;
;                         if (isk) { float s2 = (v0[0] * v0[0] + v0[1] * v0[1]) + (v0[2] * v0[2] + v0[3] * v0[3]) + (v1[0] * v1[0] + v1[1] * v1[1]) + (v1[2] * v1[2] + v1[3] * v1[3]);
;                             s2 += __shfl_xor(s2, 16); s2 += __shfl_xor(s2, 32); kmx = fmaxf(kmx, s2); }
;                         u32x4 w; w.x = pk_bf16(v0[0], v0[1]); w.y = pk_bf16(v0[2], v0[3]); w.z = pk_bf16(v1[0], v1[1]); w.w = pk_bf16(v1[2], v1[3]);
;                         *(u32x4*)(base + (size_t)row * pitch) = w;
.LBB0_325:
	v_rsq_f32_e32 v50, v48
	v_mov_b32_e32 v48, v72
	v_mov_b32_e32 v49, v72
	s_andn2_b64 vcc, exec, s[4:5]
	v_pk_fma_f32 v[52:53], v[44:45], v[50:51], v[68:69] op_sel_hi:[1,0,1]
	v_pk_fma_f32 v[44:45], v[46:47], v[50:51], v[70:71] op_sel_hi:[1,0,1]
	v_pk_mul_f32 v[46:47], v[72:73], v[52:53]
	v_pk_fma_f32 v[52:53], v[40:41], v[50:51], v[64:65] op_sel_hi:[1,0,1]
	v_pk_fma_f32 v[40:41], v[42:43], v[50:51], v[66:67] op_sel_hi:[1,0,1]
	v_pk_mul_f32 v[44:45], v[48:49], v[44:45]
	v_pk_mul_f32 v[40:41], v[48:49], v[40:41]
	v_pk_mul_f32 v[42:43], v[72:73], v[52:53]
	s_cbranch_vccnz .LBB0_327
	v_pk_mul_f32 v[48:49], v[44:45], v[44:45]
	v_pk_mul_f32 v[50:51], v[46:47], v[46:47]
	s_nop 0
	v_pk_mov_b32 v[52:53], v[50:51], v[48:49] op_sel:[1,0]
	v_mov_b32_e32 v51, v49
	v_pk_add_f32 v[48:49], v[52:53], v[50:51]
	v_pk_mul_f32 v[50:51], v[40:41], v[40:41]
	v_pk_mul_f32 v[52:53], v[42:43], v[42:43]
	v_mov_b32_e32 v54, v50
	v_mov_b32_e32 v55, v52
	v_mov_b32_e32 v52, v51
	v_pk_add_f32 v[50:51], v[54:55], v[52:53]
	v_add_f32_e32 v48, v48, v49
	v_add_f32_e32 v48, v51, v48
	v_add_f32_e32 v48, v50, v48
	v_and_b32_e32 v50, 64, v230
	v_xor_b32_e32 v49, 16, v230
	v_add_u32_e32 v50, 64, v50
	v_cmp_lt_i32_e32 vcc, v49, v50
	s_nop 1
	v_cndmask_b32_e32 v49, v230, v49, vcc
	v_lshlrev_b32_e32 v49, 2, v49
	v_mov_b32_e32 v49, v48
	s_nop 1
	v_permlane16_swap_b32_e32 v49, v48
	s_waitcnt lgkmcnt(0)
	v_add_f32_e32 v48, v48, v49
	v_xor_b32_e32 v49, 32, v230
	v_cmp_lt_i32_e32 vcc, v49, v50
	s_nop 1
	v_cndmask_b32_e32 v49, v230, v49, vcc
	v_lshlrev_b32_e32 v49, 2, v49
	v_mov_b32_e32 v49, v48
	s_nop 1
	v_permlane32_swap_b32_e32 v49, v48
	s_waitcnt lgkmcnt(0)
	v_add_f32_e32 v48, v48, v49
	v_max_f32_e32 v49, v77, v77
	v_max_f32_e32 v77, v49, v48

; __device__ __forceinline__ unsigned pk_bf16(float lo, float hi) { f32x2 v = {lo, hi}; bf16x2_t b = __builtin_convertvector(v, bf16x2_t); return __builtin_bit_cast(unsigned, b); }
;     __device__ __forceinline__ void operator()(const f32x4 (&acc)[2][2][4][2], const Unit& u, int wr, int wc, int fr, int fq) const {
;     ...
;                     for (int m = 0; m < 4; ++m) {
;                         const int row = row0 + ai * HALF + m * 16;
;                         const float rv = rsqrtf(rowss[row] * (1.0f / 1024.0f) + 1e-6f);
;                         const f32x4 v0 = (acc[ai][bj][m][0] * rv + bz0) * qsc, v1 = (acc[ai][bj][m][1] * rv + bz1) * qsc;
;                         if (isk) { float s2 = (v0[0] * v0[0] + v0[1] * v0[1]) + (v0[2] * v0[2] + v0[3] * v0[3]) + (v1[0] * v1[0] + v1[1] * v1[1]) + (v1[2] * v1[2] + v1[3] * v1[3]);
;                             s2 += __shfl_xor(s2, 16); s2 += __shfl_xor(s2, 32); kmx = fmaxf(kmx, s2); }
;                         u32x4 w; w.x = pk_bf16(v0[0], v0[1]); w.y = pk_bf16(v0[2], v0[3]); w.z = pk_bf16(v1[0], v1[1]); w.w = pk_bf16(v1[2], v1[3]);
;                         *(u32x4*)(base + (size_t)row * pitch) = w;
.LBB0_331:
	v_rsq_f32_e32 v42, v40
	v_mov_b32_e32 v40, v72
	v_mov_b32_e32 v41, v72
	s_andn2_b64 vcc, exec, s[4:5]
	v_pk_fma_f32 v[44:45], v[36:37], v[42:43], v[68:69] op_sel_hi:[1,0,1]
	v_pk_fma_f32 v[36:37], v[38:39], v[42:43], v[70:71] op_sel_hi:[1,0,1]
	v_pk_mul_f32 v[38:39], v[72:73], v[44:45]
	v_pk_fma_f32 v[44:45], v[32:33], v[42:43], v[64:65] op_sel_hi:[1,0,1]
	v_pk_fma_f32 v[32:33], v[34:35], v[42:43], v[66:67] op_sel_hi:[1,0,1]
	v_pk_mul_f32 v[36:37], v[40:41], v[36:37]
	v_pk_mul_f32 v[32:33], v[40:41], v[32:33]
	v_pk_mul_f32 v[34:35], v[72:73], v[44:45]
	s_cbranch_vccnz .LBB0_333
	v_pk_mul_f32 v[40:41], v[36:37], v[36:37]
	v_pk_mul_f32 v[42:43], v[38:39], v[38:39]
	s_nop 0
	v_pk_mov_b32 v[44:45], v[42:43], v[40:41] op_sel:[1,0]
	v_mov_b32_e32 v43, v41
	v_pk_add_f32 v[40:41], v[44:45], v[42:43]
	v_pk_mul_f32 v[42:43], v[32:33], v[32:33]
	v_pk_mul_f32 v[44:45], v[34:35], v[34:35]
	v_mov_b32_e32 v46, v42
	v_mov_b32_e32 v47, v44
	v_mov_b32_e32 v44, v43
	v_pk_add_f32 v[42:43], v[46:47], v[44:45]
	v_add_f32_e32 v40, v40, v41
	v_add_f32_e32 v40, v43, v40
	v_add_f32_e32 v40, v42, v40
	v_and_b32_e32 v42, 64, v230
	v_xor_b32_e32 v41, 16, v230
	v_add_u32_e32 v42, 64, v42
	v_cmp_lt_i32_e32 vcc, v41, v42
	s_nop 1
	v_cndmask_b32_e32 v41, v230, v41, vcc
	v_lshlrev_b32_e32 v41, 2, v41
	v_mov_b32_e32 v41, v40
	s_nop 1
	v_permlane16_swap_b32_e32 v41, v40
	s_waitcnt lgkmcnt(0)
	v_add_f32_e32 v40, v40, v41
	v_xor_b32_e32 v41, 32, v230
	v_cmp_lt_i32_e32 vcc, v41, v42
	s_nop 1
	v_cndmask_b32_e32 v41, v230, v41, vcc
	v_lshlrev_b32_e32 v41, 2, v41
	v_mov_b32_e32 v41, v40
	s_nop 1
	v_permlane32_swap_b32_e32 v41, v40
	s_waitcnt lgkmcnt(0)
	v_add_f32_e32 v40, v40, v41
	v_max_f32_e32 v41, v77, v77
	v_max_f32_e32 v77, v41, v40

; __device__ __forceinline__ unsigned pk_bf16(float lo, float hi) { f32x2 v = {lo, hi}; bf16x2_t b = __builtin_convertvector(v, bf16x2_t); return __builtin_bit_cast(unsigned, b); }
;     __device__ __forceinline__ void operator()(const f32x4 (&acc)[2][2][4][2], const Unit& u, int wr, int wc, int fr, int fq) const {
;     ...
;                     for (int m = 0; m < 4; ++m) {
;                         const int row = row0 + ai * HALF + m * 16;
;                         const float rv = rsqrtf(rowss[row] * (1.0f / 1024.0f) + 1e-6f);
;                         const f32x4 v0 = (acc[ai][bj][m][0] * rv + bz0) * qsc, v1 = (acc[ai][bj][m][1] * rv + bz1) * qsc;
;                         if (isk) { float s2 = (v0[0] * v0[0] + v0[1] * v0[1]) + (v0[2] * v0[2] + v0[3] * v0[3]) + (v1[0] * v1[0] + v1[1] * v1[1]) + (v1[2] * v1[2] + v1[3] * v1[3]);
;                             s2 += __shfl_xor(s2, 16); s2 += __shfl_xor(s2, 32); kmx = fmaxf(kmx, s2); }
;                         u32x4 w; w.x = pk_bf16(v0[0], v0[1]); w.y = pk_bf16(v0[2], v0[3]); w.z = pk_bf16(v1[0], v1[1]); w.w = pk_bf16(v1[2], v1[3]);
;                         *(u32x4*)(base + (size_t)row * pitch) = w;
.LBB0_337:
	v_rsq_f32_e32 v34, v32
	v_mov_b32_e32 v32, v72
	v_mov_b32_e32 v33, v72
	s_andn2_b64 vcc, exec, s[4:5]
	v_pk_fma_f32 v[36:37], v[28:29], v[34:35], v[68:69] op_sel_hi:[1,0,1]
	v_pk_fma_f32 v[28:29], v[30:31], v[34:35], v[70:71] op_sel_hi:[1,0,1]
	v_pk_mul_f32 v[30:31], v[72:73], v[36:37]
	v_pk_fma_f32 v[36:37], v[24:25], v[34:35], v[64:65] op_sel_hi:[1,0,1]
	v_pk_fma_f32 v[24:25], v[26:27], v[34:35], v[66:67] op_sel_hi:[1,0,1]
	v_pk_mul_f32 v[28:29], v[32:33], v[28:29]
	v_pk_mul_f32 v[24:25], v[32:33], v[24:25]
	v_pk_mul_f32 v[26:27], v[72:73], v[36:37]
	s_cbranch_vccnz .LBB0_339
	v_pk_mul_f32 v[32:33], v[28:29], v[28:29]
	v_pk_mul_f32 v[34:35], v[30:31], v[30:31]
	s_nop 0
	v_pk_mov_b32 v[36:37], v[34:35], v[32:33] op_sel:[1,0]
	v_mov_b32_e32 v35, v33
	v_pk_add_f32 v[32:33], v[36:37], v[34:35]
	v_pk_mul_f32 v[34:35], v[24:25], v[24:25]
	v_pk_mul_f32 v[36:37], v[26:27], v[26:27]
	v_mov_b32_e32 v38, v34
	v_mov_b32_e32 v39, v36
	v_mov_b32_e32 v36, v35
	v_pk_add_f32 v[34:35], v[38:39], v[36:37]
	v_add_f32_e32 v32, v32, v33
	v_add_f32_e32 v32, v35, v32
	v_add_f32_e32 v32, v34, v32
	v_and_b32_e32 v34, 64, v230
	v_xor_b32_e32 v33, 16, v230
	v_add_u32_e32 v34, 64, v34
	v_cmp_lt_i32_e32 vcc, v33, v34
	s_nop 1
	v_cndmask_b32_e32 v33, v230, v33, vcc
	v_lshlrev_b32_e32 v33, 2, v33
	v_mov_b32_e32 v33, v32
	s_nop 1
	v_permlane16_swap_b32_e32 v33, v32
	s_waitcnt lgkmcnt(0)
	v_add_f32_e32 v32, v32, v33
	v_xor_b32_e32 v33, 32, v230
	v_cmp_lt_i32_e32 vcc, v33, v34
	s_nop 1
	v_cndmask_b32_e32 v33, v230, v33, vcc
	v_lshlrev_b32_e32 v33, 2, v33
	v_mov_b32_e32 v33, v32
	s_nop 1
	v_permlane32_swap_b32_e32 v33, v32
	s_waitcnt lgkmcnt(0)
	v_add_f32_e32 v32, v32, v33
	v_max_f32_e32 v33, v77, v77
	v_max_f32_e32 v77, v33, v32

; __device__ __forceinline__ unsigned pk_bf16(float lo, float hi) { f32x2 v = {lo, hi}; bf16x2_t b = __builtin_convertvector(v, bf16x2_t); return __builtin_bit_cast(unsigned, b); }
;     __device__ __forceinline__ void operator()(const f32x4 (&acc)[2][2][4][2], const Unit& u, int wr, int wc, int fr, int fq) const {
;     ...
;                     for (int m = 0; m < 4; ++m) {
;                         const int row = row0 + ai * HALF + m * 16;
;                         const float rv = rsqrtf(rowss[row] * (1.0f / 1024.0f) + 1e-6f);
;                         const f32x4 v0 = (acc[ai][bj][m][0] * rv + bz0) * qsc, v1 = (acc[ai][bj][m][1] * rv + bz1) * qsc;
;                         if (isk) { float s2 = (v0[0] * v0[0] + v0[1] * v0[1]) + (v0[2] * v0[2] + v0[3] * v0[3]) + (v1[0] * v1[0] + v1[1] * v1[1]) + (v1[2] * v1[2] + v1[3] * v1[3]);
;                             s2 += __shfl_xor(s2, 16); s2 += __shfl_xor(s2, 32); kmx = fmaxf(kmx, s2); }
;                         u32x4 w; w.x = pk_bf16(v0[0], v0[1]); w.y = pk_bf16(v0[2], v0[3]); w.z = pk_bf16(v1[0], v1[1]); w.w = pk_bf16(v1[2], v1[3]);
;                         *(u32x4*)(base + (size_t)row * pitch) = w;
.LBB0_343:
	v_rsq_f32_e32 v26, v24
	v_mov_b32_e32 v24, v72
	v_mov_b32_e32 v25, v72
	s_andn2_b64 vcc, exec, s[4:5]
	v_pk_fma_f32 v[28:29], v[20:21], v[26:27], v[68:69] op_sel_hi:[1,0,1]
	v_pk_fma_f32 v[20:21], v[22:23], v[26:27], v[70:71] op_sel_hi:[1,0,1]
	v_pk_mul_f32 v[22:23], v[72:73], v[28:29]
	v_pk_fma_f32 v[28:29], v[16:17], v[26:27], v[64:65] op_sel_hi:[1,0,1]
	v_pk_fma_f32 v[16:17], v[18:19], v[26:27], v[66:67] op_sel_hi:[1,0,1]
	v_pk_mul_f32 v[20:21], v[24:25], v[20:21]
	v_pk_mul_f32 v[16:17], v[24:25], v[16:17]
	v_pk_mul_f32 v[18:19], v[72:73], v[28:29]
	s_cbranch_vccnz .LBB0_345
	v_pk_mul_f32 v[24:25], v[20:21], v[20:21]
	v_pk_mul_f32 v[26:27], v[22:23], v[22:23]
	s_nop 0
	v_pk_mov_b32 v[28:29], v[26:27], v[24:25] op_sel:[1,0]
	v_mov_b32_e32 v27, v25
	v_pk_add_f32 v[24:25], v[28:29], v[26:27]
	v_pk_mul_f32 v[26:27], v[16:17], v[16:17]
	v_pk_mul_f32 v[28:29], v[18:19], v[18:19]
	v_mov_b32_e32 v30, v26
	v_mov_b32_e32 v31, v28
	v_mov_b32_e32 v28, v27
	v_pk_add_f32 v[26:27], v[30:31], v[28:29]
	v_add_f32_e32 v24, v24, v25
	v_add_f32_e32 v24, v27, v24
	v_add_f32_e32 v24, v26, v24
	v_and_b32_e32 v26, 64, v230
	v_xor_b32_e32 v25, 16, v230
	v_add_u32_e32 v26, 64, v26
	v_cmp_lt_i32_e32 vcc, v25, v26
	s_nop 1
	v_cndmask_b32_e32 v25, v230, v25, vcc
	v_lshlrev_b32_e32 v25, 2, v25
	v_mov_b32_e32 v25, v24
	s_nop 1
	v_permlane16_swap_b32_e32 v25, v24
	s_waitcnt lgkmcnt(0)
	v_add_f32_e32 v24, v24, v25
	v_xor_b32_e32 v25, 32, v230
	v_cmp_lt_i32_e32 vcc, v25, v26
	s_nop 1
	v_cndmask_b32_e32 v25, v230, v25, vcc
	v_lshlrev_b32_e32 v25, 2, v25
	v_mov_b32_e32 v25, v24
	s_nop 1
	v_permlane32_swap_b32_e32 v25, v24
	s_waitcnt lgkmcnt(0)
	v_add_f32_e32 v24, v24, v25
	v_max_f32_e32 v25, v77, v77
	v_max_f32_e32 v77, v25, v24

; __device__ __forceinline__ unsigned pk_bf16(float lo, float hi) { f32x2 v = {lo, hi}; bf16x2_t b = __builtin_convertvector(v, bf16x2_t); return __builtin_bit_cast(unsigned, b); }
;     __device__ __forceinline__ void operator()(const f32x4 (&acc)[2][2][4][2], const Unit& u, int wr, int wc, int fr, int fq) const {
;     ...
;                     for (int m = 0; m < 4; ++m) {
;                         const int row = row0 + ai * HALF + m * 16;
;                         const float rv = rsqrtf(rowss[row] * (1.0f / 1024.0f) + 1e-6f);
;                         const f32x4 v0 = (acc[ai][bj][m][0] * rv + bz0) * qsc, v1 = (acc[ai][bj][m][1] * rv + bz1) * qsc;
;                         if (isk) { float s2 = (v0[0] * v0[0] + v0[1] * v0[1]) + (v0[2] * v0[2] + v0[3] * v0[3]) + (v1[0] * v1[0] + v1[1] * v1[1]) + (v1[2] * v1[2] + v1[3] * v1[3]);
;                             s2 += __shfl_xor(s2, 16); s2 += __shfl_xor(s2, 32); kmx = fmaxf(kmx, s2); }
;                         u32x4 w; w.x = pk_bf16(v0[0], v0[1]); w.y = pk_bf16(v0[2], v0[3]); w.z = pk_bf16(v1[0], v1[1]); w.w = pk_bf16(v1[2], v1[3]);
;                         *(u32x4*)(base + (size_t)row * pitch) = w;
.LBB0_349:
	v_rsq_f32_e32 v18, v16
	v_mov_b32_e32 v16, v72
	v_mov_b32_e32 v17, v72
	s_andn2_b64 vcc, exec, s[4:5]
	v_pk_fma_f32 v[20:21], v[12:13], v[18:19], v[68:69] op_sel_hi:[1,0,1]
	v_pk_fma_f32 v[12:13], v[14:15], v[18:19], v[70:71] op_sel_hi:[1,0,1]
	v_pk_mul_f32 v[14:15], v[72:73], v[20:21]
	v_pk_fma_f32 v[20:21], v[8:9], v[18:19], v[64:65] op_sel_hi:[1,0,1]
	v_pk_fma_f32 v[8:9], v[10:11], v[18:19], v[66:67] op_sel_hi:[1,0,1]
	v_pk_mul_f32 v[12:13], v[16:17], v[12:13]
	v_pk_mul_f32 v[8:9], v[16:17], v[8:9]
	v_pk_mul_f32 v[10:11], v[72:73], v[20:21]
	s_cbranch_vccnz .LBB0_351
	v_pk_mul_f32 v[16:17], v[12:13], v[12:13]
	v_pk_mul_f32 v[18:19], v[14:15], v[14:15]
	s_nop 0
	v_pk_mov_b32 v[20:21], v[18:19], v[16:17] op_sel:[1,0]
	v_mov_b32_e32 v19, v17
	v_pk_add_f32 v[16:17], v[20:21], v[18:19]
	v_pk_mul_f32 v[18:19], v[8:9], v[8:9]
	v_pk_mul_f32 v[20:21], v[10:11], v[10:11]
	v_mov_b32_e32 v22, v18
	v_mov_b32_e32 v23, v20
	v_mov_b32_e32 v20, v19
	v_pk_add_f32 v[18:19], v[22:23], v[20:21]
	v_add_f32_e32 v16, v16, v17
	v_add_f32_e32 v16, v19, v16
	v_add_f32_e32 v16, v18, v16
	v_and_b32_e32 v18, 64, v230
	v_xor_b32_e32 v17, 16, v230
	v_add_u32_e32 v18, 64, v18
	v_cmp_lt_i32_e32 vcc, v17, v18
	s_nop 1
	v_cndmask_b32_e32 v17, v230, v17, vcc
	v_lshlrev_b32_e32 v17, 2, v17
	v_mov_b32_e32 v17, v16
	s_nop 1
	v_permlane16_swap_b32_e32 v17, v16
	s_waitcnt lgkmcnt(0)
	v_add_f32_e32 v16, v16, v17
	v_xor_b32_e32 v17, 32, v230
	v_cmp_lt_i32_e32 vcc, v17, v18
	s_nop 1
	v_cndmask_b32_e32 v17, v230, v17, vcc
	v_lshlrev_b32_e32 v17, 2, v17
	v_mov_b32_e32 v17, v16
	s_nop 1
	v_permlane32_swap_b32_e32 v17, v16
	s_waitcnt lgkmcnt(0)
	v_add_f32_e32 v16, v16, v17
	v_max_f32_e32 v17, v77, v77
	v_max_f32_e32 v77, v17, v16

; __device__ __forceinline__ unsigned pk_bf16(float lo, float hi) { f32x2 v = {lo, hi}; bf16x2_t b = __builtin_convertvector(v, bf16x2_t); return __builtin_bit_cast(unsigned, b); }
;     __device__ __forceinline__ void operator()(const f32x4 (&acc)[2][2][4][2], const Unit& u, int wr, int wc, int fr, int fq) const {
;     ...
;                     for (int m = 0; m < 4; ++m) {
;                         const int row = row0 + ai * HALF + m * 16;
;                         const float rv = rsqrtf(rowss[row] * (1.0f / 1024.0f) + 1e-6f);
;                         const f32x4 v0 = (acc[ai][bj][m][0] * rv + bz0) * qsc, v1 = (acc[ai][bj][m][1] * rv + bz1) * qsc;
;                         if (isk) { float s2 = (v0[0] * v0[0] + v0[1] * v0[1]) + (v0[2] * v0[2] + v0[3] * v0[3]) + (v1[0] * v1[0] + v1[1] * v1[1]) + (v1[2] * v1[2] + v1[3] * v1[3]);
;                             s2 += __shfl_xor(s2, 16); s2 += __shfl_xor(s2, 32); kmx = fmaxf(kmx, s2); }
;                         u32x4 w; w.x = pk_bf16(v0[0], v0[1]); w.y = pk_bf16(v0[2], v0[3]); w.z = pk_bf16(v1[0], v1[1]); w.w = pk_bf16(v1[2], v1[3]);
;                         *(u32x4*)(base + (size_t)row * pitch) = w;
.LBB0_355:
	v_rsq_f32_e32 v8, v8
	v_mov_b32_e32 v12, v72
	v_mov_b32_e32 v13, v72
	s_andn2_b64 vcc, exec, s[4:5]
	v_pk_fma_f32 v[10:11], v[4:5], v[8:9], v[68:69] op_sel_hi:[1,0,1]
	v_pk_fma_f32 v[4:5], v[6:7], v[8:9], v[70:71] op_sel_hi:[1,0,1]
	v_pk_mul_f32 v[6:7], v[72:73], v[10:11]
	v_pk_fma_f32 v[10:11], v[0:1], v[8:9], v[64:65] op_sel_hi:[1,0,1]
	v_pk_fma_f32 v[0:1], v[2:3], v[8:9], v[66:67] op_sel_hi:[1,0,1]
	v_pk_mul_f32 v[4:5], v[12:13], v[4:5]
	v_pk_mul_f32 v[0:1], v[12:13], v[0:1]
	v_pk_mul_f32 v[2:3], v[72:73], v[10:11]
	s_cbranch_vccnz .LBB0_357
	v_pk_mul_f32 v[8:9], v[4:5], v[4:5]
	v_pk_mul_f32 v[10:11], v[6:7], v[6:7]
	s_nop 0
	v_pk_mov_b32 v[12:13], v[10:11], v[8:9] op_sel:[1,0]
	v_mov_b32_e32 v11, v9
	v_pk_add_f32 v[8:9], v[12:13], v[10:11]
	v_pk_mul_f32 v[10:11], v[0:1], v[0:1]
	v_pk_mul_f32 v[12:13], v[2:3], v[2:3]
	v_mov_b32_e32 v14, v10
	v_mov_b32_e32 v15, v12
	v_mov_b32_e32 v12, v11
	v_pk_add_f32 v[10:11], v[14:15], v[12:13]
	v_add_f32_e32 v8, v8, v9
	v_add_f32_e32 v8, v11, v8
	v_add_f32_e32 v8, v10, v8
	v_and_b32_e32 v10, 64, v230
	v_xor_b32_e32 v9, 16, v230
	v_add_u32_e32 v10, 64, v10
	v_cmp_lt_i32_e32 vcc, v9, v10
	s_nop 1
	v_cndmask_b32_e32 v9, v230, v9, vcc
	v_lshlrev_b32_e32 v9, 2, v9
	v_mov_b32_e32 v9, v8
	s_nop 1
	v_permlane16_swap_b32_e32 v9, v8
	s_waitcnt lgkmcnt(0)
	v_add_f32_e32 v8, v8, v9
	v_xor_b32_e32 v9, 32, v230
	v_cmp_lt_i32_e32 vcc, v9, v10
	s_nop 1
	v_cndmask_b32_e32 v9, v230, v9, vcc
	v_lshlrev_b32_e32 v9, 2, v9
	v_mov_b32_e32 v9, v8
	s_nop 1
	v_permlane32_swap_b32_e32 v9, v8
	s_waitcnt lgkmcnt(0)
	v_add_f32_e32 v8, v8, v9
	v_max_f32_e32 v9, v77, v77
	v_max_f32_e32 v77, v9, v8

;     __device__ __forceinline__ void operator()(const f32x4 (&acc)[2][2][4][2], const Unit& u, int wr, int wc, int fr, int fq) const {
;     ...
;                 if (isk) { kmx = fmaxf(kmx, __shfl_xor(kmx, 1)); kmx = fmaxf(kmx, __shfl_xor(kmx, 2)); kmx = fmaxf(kmx, __shfl_xor(kmx, 4)); kmx = fmaxf(kmx, __shfl_xor(kmx, 8));
;                     if (fr == 0 && fqo == 0) { const int grp = pn == 1 ? 0 : 1; const int head = pn == 1 ? bj * 2 + (wc >> 1) : (wc >> 1);
;                         atomicMax(kmax + (grp * 4 + head) * 2 + (wc & 1), __float_as_uint(kmx * 1.02f)); } }
.LBB0_361:
	s_andn2_b64 vcc, exec, s[0:1]
	s_cbranch_vccnz .LBB0_368
	v_and_b32_e32 v1, 64, v230
	v_xor_b32_e32 v0, 1, v230
	v_add_u32_e32 v1, 64, v1
	v_cmp_lt_i32_e32 vcc, v0, v1
	v_max_f32_e32 v2, v77, v77
	s_nop 0
	v_cndmask_b32_e32 v0, v230, v0, vcc
	v_lshlrev_b32_e32 v0, 2, v0
	s_nop 1
	v_mov_b32_dpp v0, v77 quad_perm:[1,0,3,2] row_mask:0xf bank_mask:0xf
	s_waitcnt lgkmcnt(0)
	v_max_f32_e32 v0, v0, v0
	v_max_f32_e32 v0, v2, v0
	v_xor_b32_e32 v2, 2, v230
	v_cmp_lt_i32_e32 vcc, v2, v1
	s_nop 1
	v_cndmask_b32_e32 v2, v230, v2, vcc
	v_lshlrev_b32_e32 v2, 2, v2
	s_nop 1
	v_mov_b32_dpp v2, v0 quad_perm:[2,3,0,1] row_mask:0xf bank_mask:0xf
	s_waitcnt lgkmcnt(0)
	v_max_f32_e32 v2, v2, v2
	v_max_f32_e32 v0, v0, v2
	v_xor_b32_e32 v2, 4, v230
	v_cmp_lt_i32_e32 vcc, v2, v1
	s_nop 1
	v_cndmask_b32_e32 v2, v230, v2, vcc
	v_lshlrev_b32_e32 v2, 2, v2
	s_nop 1
	v_mov_b32_dpp v2, v0 row_half_mirror row_mask:0xf bank_mask:0xf
	s_waitcnt lgkmcnt(0)
	v_max_f32_e32 v2, v2, v2
	v_max_f32_e32 v0, v0, v2
	v_xor_b32_e32 v2, 8, v230
	v_cmp_lt_i32_e32 vcc, v2, v1
	s_nop 1
	v_cndmask_b32_e32 v1, v230, v2, vcc
	v_lshlrev_b32_e32 v1, 2, v1
	s_nop 1
	v_mov_b32_dpp v1, v0 row_mirror row_mask:0xf bank_mask:0xf
	s_and_saveexec_b64 s[0:1], s[70:71]
	s_cbranch_execz .LBB0_367
	s_waitcnt lgkmcnt(0)
	v_max_f32_e32 v1, v1, v1
	v_max_f32_e32 v0, v0, v0
	v_max_f32_e32 v0, v0, v1
	s_mov_b64 s[4:5], exec
	v_mul_f32_e32 v0, 0x3f828f5c, v0
	s_mov_b32 s6, 0
